# v21: mixer workgroups start phase 3 about 11 us late (3 x s_sleep 127) so GLA pass A has the HBM to itself
# baseline (speedup 1.0000x reference)
; __device__ __forceinline__ void phase_mixer_a(const Params& P, LAS unsigned char* lds, int ustart, int ustride, bool dry) {
;     const int tid = opaque_tid(), lane = tid & 63, w = tid >> 6, g4 = lane >> 4, q = (lane & 15) >> 2, p = lane & 3;
;     bf16_t* PJ = (bf16_t*)(P.ws + WS_PJ); const bf16_t* WsT = (const bf16_t*)(P.ws + WS_WST);
;     constexpr int VN_P = 288, W_P = 272, W_OFF = 128 * VN_P, ST_OFF = W_OFF + 128 * W_P;
;     LAS float* stats = (LAS float*)(lds + ST_OFF);
;     for (int unit = ustart; unit < NTOK / 128; unit += ustride) {
;         const int r0 = unit * 128;
;         for (int i0 = 0; i0 < 16; i0 += 4) {
;             u32x4 ra[4], rb[4];
; #pragma unroll
;             for (int q4 = 0; q4 < 4; ++q4) { const u32x4* gp = (const u32x4*)(PJ + T_GV + (size_t)(r0 + 16 * w + i0 + q4) * 1024); ra[q4] = gp[lane]; rb[q4] = gp[lane + 64]; }
; #pragma unroll
;             for (int q4 = 0; q4 < 4; ++q4) {
;                 const int s = 16 * w + i0 + q4; const u32x4 a = ra[q4], b = rb[q4];
;                 float x[16] = {bflo(a.x), bfhi(a.x), bflo(a.y), bfhi(a.y), bflo(a.z), bfhi(a.z), bflo(a.w), bfhi(a.w), bflo(b.x), bfhi(b.x), bflo(b.y), bfhi(b.y), bflo(b.z), bfhi(b.z), bflo(b.w), bfhi(b.w)};
;                 float sm = 0.f;
; #pragma unroll
;                 for (int j = 0; j < 16; ++j) sm += x[j];
;                 const float mean = wave_sum(sm) * (1.0f / 1024.0f); float sq = 0.f;
; #pragma unroll
;                 for (int j = 0; j < 16; ++j) { const float d = x[j] - mean; sq += d * d; }
;                 const float rstd = 1.0f / sqrtf(wave_sum(sq) * (1.0f / 1024.0f) + LN_EPS);
;                 if (lane == 0) { stats[2 * s] = mean; stats[2 * s + 1] = rstd; }
;             }
;         }
;         __syncthreads();
;         u32x4 pgv[4];
; #pragma unroll
;         for (int i = 0; i < 4; ++i) { const int item = tid + 512 * i, c8 = item & 15, s = item >> 4;
;             pgv[i] = *(const u32x4*)(PJ + T_GV + (size_t)(r0 + s) * 1024 + c8 * 8); }
; __device__ __forceinline__ void phase_scan_and_mixer(const Params& P, LAS unsigned char* lds, bool dry) {
;     ...
;     if (NG) {
;         if ((int)blockIdx.x < NG) { const int seg = blockIdx.x >> 5, bh = blockIdx.x & 31; gla_scan(P, lds, bh, seg, 4, dry); }
;         else { phase_mixer_a(P, lds, blockIdx.x - NG, G - NG, dry); phase_branch_weights(P, lds, blockIdx.x - NG, G - NG); }
.LBB0_615:
	s_and_b64 vcc, exec, s[4:5]
	s_cbranch_vccz .LBB0_714
	s_cmpk_gt_i32 s2, 0x7f
	s_mov_b64 s[4:5], -1
	s_cbranch_scc0 .LBB0_652
	s_add_i32 s1, s2, 0xffffff80
	s_add_i32 s0, s38, 0xffffff80
	s_sleep 127
	s_sleep 127
	s_sleep 127
	s_waitcnt vmcnt(2)
	v_mov_b32_e32 v0, v194
	s_cmpk_gt_u32 s1, 0xff
	s_cbranch_scc1 .LBB0_634
	v_mbcnt_hi_u32_b32 v3, -1, v195
	v_and_b32_e32 v4, 64, v3
	v_add_u32_e32 v4, 64, v4
	v_xor_b32_e32 v5, 1, v3
	v_cmp_lt_i32_e32 vcc, v5, v4
	v_mov_b32_e32 v33, 0
	v_ashrrev_i32_e32 v14, 6, v0
	v_cndmask_b32_e32 v5, v3, v5, vcc
	v_lshlrev_b32_e32 v132, 2, v5
	v_xor_b32_e32 v5, 2, v3
	v_cmp_lt_i32_e32 vcc, v5, v4
	s_mov_b64 s[6:7], 0x6000000
	v_and_b32_e32 v12, 15, v0
	v_cndmask_b32_e32 v5, v3, v5, vcc
	v_lshlrev_b32_e32 v133, 2, v5
	v_xor_b32_e32 v5, 4, v3
	v_cmp_lt_i32_e32 vcc, v5, v4
	v_bfe_u32 v1, v0, 2, 2
	v_and_b32_e32 v13, 63, v0
	v_cndmask_b32_e32 v5, v3, v5, vcc
	v_lshlrev_b32_e32 v134, 2, v5
	v_xor_b32_e32 v5, 8, v3
	v_cmp_lt_i32_e32 vcc, v5, v4
	v_ashrrev_i32_e32 v138, 4, v0
	v_add_u32_e32 v8, 0x400, v0
	v_cndmask_b32_e32 v5, v3, v5, vcc
	v_lshlrev_b32_e32 v135, 2, v5
	v_xor_b32_e32 v5, 16, v3
	v_cmp_lt_i32_e32 vcc, v5, v4
	v_add_u32_e32 v10, 0x600, v0
	v_ashrrev_i32_e32 v140, 4, v8
	v_cndmask_b32_e32 v5, v3, v5, vcc
	v_lshlrev_b32_e32 v136, 2, v5
	v_xor_b32_e32 v5, 32, v3
	v_cmp_lt_i32_e32 vcc, v5, v4
	v_lshlrev_b32_e32 v4, 3, v0
	v_ashrrev_i32_e32 v141, 4, v10
	v_cndmask_b32_e32 v3, v3, v5, vcc
	v_lshlrev_b32_e32 v137, 2, v3
	v_lshlrev_b32_e32 v3, 4, v0
	v_and_b32_e32 v32, 0xf0, v3
	v_lshl_add_u64 v[6:7], s[70:71], 0, v[32:33]
	v_lshrrev_b32_e32 v5, 1, v0
	v_lshl_add_u64 v[34:35], v[6:7], 0, s[6:7]
	v_and_b32_e32 v16, 24, v5
	v_lshlrev_b32_e32 v5, 5, v14
	v_and_b32_e32 v6, 24, v4
	v_add3_u32 v17, 0, v5, v6
	v_add_u32_e32 v6, 0x200, v0
	v_and_b32_e32 v0, 48, v0
	s_movk_i32 s6, 0x110
	v_add_u32_e32 v142, 0, v0
	v_mov_b32_e32 v0, 0x1100
	v_mad_u32_u24 v144, v12, s6, v0
	v_or_b32_e32 v0, 32, v16
	v_or_b32_e32 v31, v0, v1
	v_lshl_add_u32 v145, v0, 1, 0
	v_or_b32_e32 v0, 64, v16
	v_ashrrev_i32_e32 v139, 4, v6
	s_movk_i32 s3, 0x120
	v_or_b32_e32 v36, v0, v1
	v_lshl_add_u32 v146, v0, 1, 0
	v_or_b32_e32 v0, 0x60, v16
	v_lshlrev_b32_e32 v2, 4, v14
	v_mul_lo_u32 v19, v138, s3
	v_mul_lo_u32 v22, v139, s3
	v_mul_lo_u32 v25, v140, s3
	v_mul_lo_u32 v28, v141, s3
	v_or_b32_e32 v30, v16, v1
	v_or_b32_e32 v1, v0, v1
	v_lshl_add_u32 v147, v0, 1, 0
	v_lshl_add_u32 v0, v14, 7, 0
	s_lshl_b32 s3, s2, 7
	v_add_u32_e32 v148, 0x11800, v0
	v_add_u32_e32 v0, s3, v2
	v_add_u32_e32 v0, 0xffffc000, v0
	v_mul_u32_u24_e32 v43, 0x120, v1
	v_ashrrev_i32_e32 v1, 31, v0
	v_lshlrev_b64 v[0:1], 11, v[0:1]
	v_lshl_or_b32 v0, v13, 4, v0
	v_mul_lo_u32 v20, v138, s6
	v_mul_lo_u32 v23, v139, s6
	v_mul_lo_u32 v26, v140, s6
	v_mul_lo_u32 v29, v141, s6
	v_lshl_add_u64 v[0:1], s[70:71], 0, v[0:1]
	s_mov_b64 s[6:7], 0x6001c00
	v_lshlrev_b32_e32 v32, 4, v12
	v_mul_u32_u24_e32 v41, 0x120, v36
	v_lshl_add_u64 v[36:37], v[0:1], 0, s[6:7]
	s_lshl_b32 s6, s38, 7
	s_add_i32 s8, s6, 0xffffc000
	v_lshl_add_u64 v[0:1], s[70:71], 0, v[32:33]
	s_mov_b64 s[6:7], 0x6000100
	v_lshl_add_u64 v[38:39], v[0:1], 0, s[6:7]
	v_add_u32_e32 v0, s3, v138
	v_add_u32_e32 v40, 0xffffc000, v0
	v_add_u32_e32 v0, s3, v139
	v_add_u32_e32 v42, 0xffffc000, v0
	v_add_u32_e32 v0, s3, v140
	v_ashrrev_i32_e32 v5, 31, v4
	v_lshlrev_b32_e32 v6, 3, v6
	v_add_u32_e32 v44, 0xffffc000, v0
	v_add_u32_e32 v0, s3, v141
	v_ashrrev_i32_e32 v7, 31, v6
	v_lshlrev_b32_e32 v8, 3, v8
	v_add_u32_e32 v46, 0xffffc000, v0
	v_lshl_add_u64 v[0:1], v[4:5], 1, s[70:71]
	s_mov_b64 s[6:7], 0x1700000
	v_ashrrev_i32_e32 v9, 31, v8
	v_lshlrev_b32_e32 v10, 3, v10
	v_lshl_add_u64 v[48:49], v[0:1], 0, s[6:7]
	v_lshl_add_u64 v[0:1], v[6:7], 1, s[70:71]
	v_ashrrev_i32_e32 v11, 31, v10
	v_lshl_add_u64 v[50:51], v[0:1], 0, s[6:7]
	v_lshl_add_u64 v[0:1], v[8:9], 1, s[70:71]
	v_ashrrev_i32_e32 v3, 31, v2
	v_lshl_add_u64 v[52:53], v[0:1], 0, s[6:7]
	v_lshl_add_u64 v[0:1], v[10:11], 1, s[70:71]
	v_lshl_add_u64 v[54:55], v[0:1], 0, s[6:7]
	v_lshlrev_b64 v[0:1], 1, v[2:3]
	v_or_b32_e32 v0, v0, v16
	v_add_u32_e32 v15, 0, v32
	v_lshl_add_u64 v[56:57], s[68:69], 0, v[0:1]
	v_or_b32_e32 v2, s3, v12
	v_lshlrev_b32_e32 v32, 2, v12
	v_lshl_add_u64 v[0:1], s[70:71], 0, v[0:1]
	s_mov_b64 s[6:7], 0x2000000
	v_lshlrev_b32_e32 v18, 3, v138
	v_lshlrev_b32_e32 v21, 3, v139
	v_lshlrev_b32_e32 v24, 3, v140
	v_lshlrev_b32_e32 v27, 3, v141
	v_mul_u32_u24_e32 v30, 0x120, v30
	v_mul_u32_u24_e32 v31, 0x120, v31
	s_ashr_i32 s9, s8, 31
	v_add_u32_e32 v3, 0xffffc070, v2
	v_lshl_add_u64 v[58:59], s[52:53], 0, v[32:33]
	v_lshl_or_b32 v32, v12, 5, 16
	v_lshl_add_u64 v[68:69], v[0:1], 0, s[6:7]
	s_add_i32 s6, 0, 0x11800
	v_cmp_eq_u32_e64 s[4:5], 0, v13
	v_mul_u32_u24_e32 v143, 0x110, v12
	s_lshl_b64 s[10:11], s[8:9], 11
	v_add_u32_e32 v60, 0xffffc060, v2
	v_lshl_add_u64 v[62:63], s[46:47], 0, v[32:33]
	v_add_u32_e32 v64, 0xffffc050, v2
	v_lshl_add_u64 v[66:67], s[48:49], 0, v[32:33]
	v_add_u32_e32 v70, 0xffffc000, v2
	v_add_u32_e32 v72, 0xffffc010, v2
	v_add_u32_e32 v74, 0xffffc020, v2
	v_add_u32_e32 v76, 0xffffc030, v2
	v_add_u32_e32 v78, 0xffffc040, v2
	s_mov_b32 s3, 0xffff0000
	v_mov_b32_e32 v149, 0x3727c5ac
	s_mov_b32 s9, 0xf800000
	v_mov_b32_e32 v150, 0x260
	s_mov_b64 s[12:13], 0x2000
	v_add_u32_e32 v151, s6, v18
	s_movk_i32 s18, 0x7fff
	v_add_u32_e32 v152, v15, v19
	v_add_u32_e32 v153, v15, v20
	v_add_u32_e32 v154, s6, v21
	v_add_u32_e32 v155, v15, v22
	v_add_u32_e32 v156, v15, v23
	v_add_u32_e32 v157, s6, v24
	v_add_u32_e32 v158, v15, v25
	v_add_u32_e32 v159, v15, v26
	v_add_u32_e32 v160, s6, v27
	v_add_u32_e32 v161, v15, v28
	v_add_u32_e32 v162, v15, v29
	v_add_u32_e32 v163, v17, v30
	v_add_u32_e32 v164, v17, v31
	v_add_u32_e32 v165, v17, v41
	v_add_u32_e32 v166, v17, v43
	s_mov_b64 s[14:15], 0x8000
	v_mov_b32_e32 v167, 1
	v_mov_b32_e32 v32, v3
	s_mov_b32 s19, s1
	s_branch .LBB0_620
